# v73 + DPP reductions in LRU pass 2 (per-token sum of squares) and in the attention exit-bound max
# speedup vs baseline: 1.0073x; 1.0013x over previous
.LBB0_383:
	s_or_b64 exec, exec, s[28:29]
	s_nop 6
	v_max3_f32 v0, v80, v81, v82
	v_max3_f32 v2, v83, v84, v85
	v_max3_f32 v3, v86, v87, v88
	v_max3_f32 v4, v89, v90, v91
	v_max3_f32 v5, v92, v93, v94
	v_max3_f32 v6, v95, v96, v97
	v_max3_f32 v7, v98, v99, v100
	v_max3_f32 v8, v101, v102, v103
	v_max3_f32 v9, v104, v105, v106
	v_max3_f32 v10, v107, v108, v109
	v_max3_f32 v11, v110, v111, v0
	v_max3_f32 v2, v2, v3, v4
	v_max3_f32 v5, v5, v6, v7
	v_max3_f32 v8, v8, v9, v10
	v_max3_f32 v2, v2, v5, v8
	v_max_f32_e32 v0, v2, v11
	v_mov_b32_e32 v2, v0
	s_nop 1
	v_permlane32_swap_b32_e32 v0, v2
	v_max3_f32 v222, v221, v0, v2
	v_sub_f32_e32 v0, v221, v222
	v_exp_f32_e32 v0, v0
	s_nop 0
	v_cmp_eq_f32_e32 vcc, 1.0, v0
	s_cmp_lg_u64 vcc, exec
	s_cselect_b64 s[28:29], -1, 0
	s_cmp_eq_u64 vcc, exec
	s_cbranch_scc1 .LBB0_385
	v_sub_f32_e32 v2, v210, v222
	s_nop 1
	v_max_f32_dpp v2, v2, v2 quad_perm:[1,0,3,2] row_mask:0xf bank_mask:0xf
	s_nop 1
	v_max_f32_dpp v2, v2, v2 quad_perm:[2,3,0,1] row_mask:0xf bank_mask:0xf
	s_nop 1
	v_max_f32_dpp v2, v2, v2 row_half_mirror row_mask:0xf bank_mask:0xf
	s_nop 1
	v_max_f32_dpp v2, v2, v2 row_mirror row_mask:0xf bank_mask:0xf
	v_mov_b32_e32 v3, v2
	s_nop 1
	v_permlane16_swap_b32 v3, v2
	v_max_f32_e32 v219, v2, v3

.LBB0_443:
	s_or_b64 exec, exec, s[28:29]
	s_nop 6
	v_max3_f32 v0, v80, v81, v82
	v_max3_f32 v2, v83, v84, v85
	v_max3_f32 v3, v86, v87, v88
	v_max3_f32 v4, v89, v90, v91
	v_max3_f32 v5, v92, v93, v94
	v_max3_f32 v6, v95, v96, v97
	v_max3_f32 v7, v98, v99, v100
	v_max3_f32 v8, v101, v102, v103
	v_max3_f32 v9, v104, v105, v106
	v_max3_f32 v10, v107, v108, v109
	v_max3_f32 v11, v110, v111, v0
	v_max3_f32 v2, v2, v3, v4
	v_max3_f32 v5, v5, v6, v7
	v_max3_f32 v8, v8, v9, v10
	v_max3_f32 v2, v2, v5, v8
	v_max_f32_e32 v0, v2, v11
	v_mov_b32_e32 v2, v0
	s_nop 1
	v_permlane32_swap_b32_e32 v0, v2
	v_max3_f32 v215, v214, v0, v2
	v_sub_f32_e32 v0, v214, v215
	v_exp_f32_e32 v0, v0
	s_nop 0
	v_cmp_eq_f32_e32 vcc, 1.0, v0
	s_cmp_lg_u64 vcc, exec
	s_cselect_b64 s[28:29], -1, 0
	s_cmp_eq_u64 vcc, exec
	s_cbranch_scc1 .LBB0_445
	v_sub_f32_e32 v2, v202, v215
	s_nop 1
	v_max_f32_dpp v2, v2, v2 quad_perm:[1,0,3,2] row_mask:0xf bank_mask:0xf
	s_nop 1
	v_max_f32_dpp v2, v2, v2 quad_perm:[2,3,0,1] row_mask:0xf bank_mask:0xf
	s_nop 1
	v_max_f32_dpp v2, v2, v2 row_half_mirror row_mask:0xf bank_mask:0xf
	s_nop 1
	v_max_f32_dpp v2, v2, v2 row_mirror row_mask:0xf bank_mask:0xf
	v_mov_b32_e32 v3, v2
	s_nop 1
	v_permlane16_swap_b32 v3, v2
	v_max_f32_e32 v212, v2, v3

.LBB0_650:
	s_or_b64 exec, exec, s[2:3]
	ds_read2st64_b32 v[110:111], v184 offset0:196 offset1:198
	ds_read2st64_b32 v[120:121], v184 offset0:200 offset1:202
	ds_read_b32 v109, v185
	ds_read_b32 v122, v186
	ds_read_b32 v123, v187
	ds_read_b32 v124, v189
	ds_read_b32 v125, v190
	ds_read_b32 v126, v191
	ds_read_b32 v127, v192
	ds_read_b32 v128, v193
	s_waitcnt lgkmcnt(7)
	v_fmac_f32_e32 v109, v88, v110
	s_waitcnt lgkmcnt(6)
	v_fmac_f32_e32 v122, v109, v111
	ds_read2st64_b32 v[110:111], v184 offset0:204 offset1:206
	s_waitcnt lgkmcnt(6)
	v_fmac_f32_e32 v123, v122, v120
	s_waitcnt lgkmcnt(5)
	v_fmac_f32_e32 v124, v123, v121
	ds_read2st64_b32 v[120:121], v184 offset0:208 offset1:210
	ds_write_b32 v185, v109
	s_waitcnt lgkmcnt(2)
	v_fmac_f32_e32 v125, v124, v110
	v_fmac_f32_e32 v126, v125, v111
	ds_write_b32 v186, v122
	s_waitcnt lgkmcnt(2)
	v_fmac_f32_e32 v127, v126, v120
	v_fmac_f32_e32 v128, v127, v121
	ds_write_b32 v187, v123
	ds_write_b32 v189, v124
	ds_write_b32 v190, v125
	ds_write_b32 v191, v126
	ds_write_b32 v192, v127
	ds_write_b32 v193, v128
	ds_read2st64_b32 v[110:111], v184 offset0:212 offset1:214
	ds_read2st64_b32 v[120:121], v184 offset0:216 offset1:218
	ds_read_b32 v88, v194
	ds_read_b32 v109, v195
	ds_read_b32 v122, v196
	ds_read_b32 v123, v197
	ds_read_b32 v124, v198
	ds_read_b32 v125, v199
	ds_read_b32 v126, v200
	ds_read_b32 v127, v201
	s_waitcnt lgkmcnt(7)
	v_fmac_f32_e32 v88, v128, v110
	s_waitcnt lgkmcnt(6)
	v_fmac_f32_e32 v109, v88, v111
	ds_read2st64_b32 v[110:111], v184 offset0:220 offset1:222
	s_waitcnt lgkmcnt(6)
	v_fmac_f32_e32 v122, v109, v120
	s_waitcnt lgkmcnt(5)
	v_fmac_f32_e32 v123, v122, v121
	ds_read2st64_b32 v[120:121], v184 offset0:224 offset1:226
	ds_write_b32 v194, v88
	s_waitcnt lgkmcnt(2)
	v_fmac_f32_e32 v124, v123, v110
	v_fmac_f32_e32 v125, v124, v111
	ds_write_b32 v195, v109
	s_waitcnt lgkmcnt(2)
	v_fmac_f32_e32 v126, v125, v120
	v_fmac_f32_e32 v127, v126, v121
	ds_write_b32 v196, v122
	ds_write_b32 v197, v123
	ds_write_b32 v198, v124
	ds_write_b32 v199, v125
	ds_write_b32 v200, v126
	ds_write_b32 v201, v127
	s_waitcnt lgkmcnt(0)
	s_barrier
	ds_read_b128 v[132:135], v157
	ds_read_b128 v[128:131], v157 offset:16
	ds_read_b128 v[124:127], v157 offset:32
	ds_read_b128 v[120:123], v157 offset:48
	s_waitcnt lgkmcnt(3)
	v_mul_f32_e32 v88, v133, v133
	v_fmac_f32_e32 v88, v132, v132
	v_fmac_f32_e32 v88, v134, v134
	v_fmac_f32_e32 v88, v135, v135
	s_waitcnt lgkmcnt(2)
	v_fmac_f32_e32 v88, v128, v128
	v_fmac_f32_e32 v88, v129, v129
	v_fmac_f32_e32 v88, v130, v130
	v_fmac_f32_e32 v88, v131, v131
	s_waitcnt lgkmcnt(1)
	v_fmac_f32_e32 v88, v124, v124
	v_fmac_f32_e32 v88, v125, v125
	v_fmac_f32_e32 v88, v126, v126
	v_fmac_f32_e32 v88, v127, v127
	s_waitcnt lgkmcnt(0)
	v_fmac_f32_e32 v88, v120, v120
	v_fmac_f32_e32 v88, v121, v121
	v_fmac_f32_e32 v88, v122, v122
	v_fmac_f32_e32 v88, v123, v123
	s_nop 1
	v_add_f32_dpp v88, v88, v88 quad_perm:[1,0,3,2] row_mask:0xf bank_mask:0xf
	s_nop 1
	v_add_f32_dpp v88, v88, v88 quad_perm:[2,3,0,1] row_mask:0xf bank_mask:0xf
	s_nop 1
	v_add_f32_dpp v88, v88, v88 row_half_mirror row_mask:0xf bank_mask:0xf
	s_waitcnt vmcnt(0)
	s_and_saveexec_b64 s[2:3], vcc
	s_cbranch_execz .LBB0_627
	v_lshl_add_u64 v[110:111], v[148:149], 2, s[18:19]
	global_atomic_add_f32 v[110:111], v88, off
	s_branch .LBB0_627
